# LN1 phase: MFMA A/B swapped (C^T fragments) + hand-written LayerNorm epilogue: no LDS staging, dwordx4 residual loads all in flight, permlane reduce-scatter row stats, dwordx4/x2 stores
# speedup vs baseline: 1.0187x; 1.0187x over previous
.LBB0_94:
	s_mul_hi_u32 s23, s19, 0xaaaaaaab
	s_lshr_b32 s23, s23, 1
	s_mul_i32 s23, s23, 0x24000
	s_waitcnt lgkmcnt(0)
	v_mfma_f32_16x16x32_bf16 v[66:69], v[22:25], v[26:29], v[66:69]
	v_add_u32_e32 v222, s13, v113
	s_mul_hi_u32 s27, s14, 0xaaaaaaab
	s_lshr_b32 s27, s27, 1
	v_mfma_f32_16x16x32_bf16 v[62:65], v[18:21], v[26:29], v[62:65]
	s_mul_i32 s27, s27, 0x24000
	v_subrev_u32_e32 v182, s27, v126
	v_subrev_u32_e32 v191, s27, v127
	v_mfma_f32_16x16x32_bf16 v[58:61], v[10:13], v[26:29], v[58:61]
	v_subrev_u32_e32 v201, s27, v128
	v_mfma_f32_16x16x32_bf16 v[54:57], v[6:9], v[26:29], v[54:57]
	v_subrev_u32_e32 v26, s23, v125
	v_mfma_f32_16x16x32_bf16 v[50:53], v[22:25], v[14:17], v[50:53]
	v_mfma_f32_16x16x32_bf16 v[46:49], v[18:21], v[14:17], v[46:49]
	v_mfma_f32_16x16x32_bf16 v[42:45], v[10:13], v[14:17], v[42:45]
	v_mfma_f32_16x16x32_bf16 v[38:41], v[6:9], v[14:17], v[38:41]
	v_subrev_u32_e32 v14, s23, v129
	v_add_u32_e32 v16, v222, v26
	v_add_u32_e32 v14, v222, v14
	v_mfma_f32_16x16x32_bf16 v[34:37], v[22:25], v[30:33], v[34:37]
	v_subrev_u32_e32 v15, s27, v130
	v_mfma_f32_16x16x32_bf16 v[86:89], v[22:25], v[2:5], v[86:89]
	ds_read_b128 v[22:25], v16
	ds_read_b128 v[174:177], v16 offset:2048
	ds_read_b128 v[178:181], v16 offset:4096
	ds_read_b128 v[202:205], v16 offset:6144
	ds_read_b128 v[206:209], v14 offset:32768
	ds_read_b128 v[210:213], v14 offset:34816
	ds_read_b128 v[214:217], v14 offset:36864
	ds_read_b128 v[218:221], v14 offset:38912
	v_mfma_f32_16x16x32_bf16 v[74:77], v[18:21], v[30:33], v[74:77]
	v_mfma_f32_16x16x32_bf16 v[70:73], v[10:13], v[30:33], v[70:73]
	v_mfma_f32_16x16x32_bf16 v[78:81], v[6:9], v[30:33], v[78:81]
	v_mfma_f32_16x16x32_bf16 v[94:97], v[18:21], v[2:5], v[94:97]
	v_mfma_f32_16x16x32_bf16 v[90:93], v[10:13], v[2:5], v[90:93]
	v_mfma_f32_16x16x32_bf16 v[82:85], v[6:9], v[2:5], v[82:85]
	s_add_i32 s23, s6, 4
	s_mul_i32 s27, s23, 0xab
	s_bfe_u32 s27, s27, 0x70009
	s_mul_i32 s27, s27, 3
	s_sub_i32 s23, s23, s27
	s_and_b32 s23, s23, 0xff
	s_mul_i32 s23, s23, 0xc000
	s_waitcnt vmcnt(6)
	v_add_u32_e32 v2, v222, v15
	v_add_u32_e32 v6, v222, v201
	s_waitcnt lgkmcnt(0)
	v_mfma_f32_16x16x32_bf16 v[66:69], v[206:209], v[174:177], v[66:69]
	s_mov_b64 s[46:47], 0xbdd8180
	s_add_i32 s27, s23, s8
	s_waitcnt lgkmcnt(0)
	v_mfma_f32_16x16x32_bf16 v[62:65], v[210:213], v[174:177], v[62:65]
	s_barrier
	ds_read_b128 v[30:33], v2
	ds_read_b128 v[26:29], v2 offset:2048
	ds_read_b128 v[14:17], v2 offset:4096
	ds_read_b128 v[2:5], v2 offset:6144
	v_mfma_f32_16x16x32_bf16 v[58:61], v[214:217], v[174:177], v[58:61]
	v_add_u32_e32 v7, v222, v191
	s_mov_b32 m0, s27
	s_add_i32 s23, s23, s9
	v_mfma_f32_16x16x32_bf16 v[54:57], v[218:221], v[174:177], v[54:57]
	v_lshl_add_u64 v[174:175], v[108:109], 0, v[98:99]
	v_lshl_add_u64 v[176:177], v[174:175], 0, s[46:47]
	s_mov_b64 s[46:47], 0xbddc180
	v_mfma_f32_16x16x32_bf16 v[34:37], v[206:209], v[22:25], v[34:37]
	s_add_i32 s19, s19, 1
	v_mfma_f32_16x16x32_bf16 v[74:77], v[210:213], v[22:25], v[74:77]
	v_mfma_f32_16x16x32_bf16 v[70:73], v[214:217], v[22:25], v[70:73]
	v_mfma_f32_16x16x32_bf16 v[78:81], v[218:221], v[22:25], v[78:81]
	ds_read_b128 v[22:25], v6
	ds_read_b128 v[18:21], v7
	v_add_u32_e32 v6, v222, v182
	ds_read_b128 v[10:13], v6
	ds_read_b128 v[6:9], v6 offset:2048
	global_load_lds_dwordx4 v[176:177], off
	v_lshl_add_u64 v[176:177], v[174:175], 0, s[46:47]
	s_add_i32 m0, s27, 0x400
	s_mov_b64 s[46:47], 0xbde0180
	global_load_lds_dwordx4 v[176:177], off
	v_lshl_add_u64 v[176:177], v[174:175], 0, s[46:47]
	s_add_i32 m0, s27, 0x800
	s_mov_b64 s[46:47], 0xbde4180
	global_load_lds_dwordx4 v[176:177], off
	v_lshl_add_u64 v[174:175], v[174:175], 0, s[46:47]
	s_add_i32 m0, s27, 0xc00
	s_mov_b64 s[46:47], 0x1b00180
	global_load_lds_dwordx4 v[174:175], off
	v_lshl_add_u64 v[174:175], v[110:111], 0, v[98:99]
	v_lshl_add_u64 v[176:177], v[174:175], 0, s[46:47]
	s_add_i32 m0, s23, 0x8000
	s_mov_b64 s[46:47], 0x1b04180
	global_load_lds_dwordx4 v[176:177], off
	v_lshl_add_u64 v[174:175], v[174:175], 0, s[46:47]
	s_add_i32 m0, s23, 0x8400
	v_mfma_f32_16x16x32_bf16 v[50:53], v[206:209], v[178:181], v[50:53]
	global_load_lds_dwordx4 v[174:175], off
	v_mfma_f32_16x16x32_bf16 v[46:49], v[210:213], v[178:181], v[46:49]
	v_mfma_f32_16x16x32_bf16 v[42:45], v[214:217], v[178:181], v[42:45]
	v_mfma_f32_16x16x32_bf16 v[38:41], v[218:221], v[178:181], v[38:41]
	v_mfma_f32_16x16x32_bf16 v[86:89], v[206:209], v[202:205], v[86:89]
	v_mfma_f32_16x16x32_bf16 v[94:97], v[210:213], v[202:205], v[94:97]
	v_mfma_f32_16x16x32_bf16 v[90:93], v[214:217], v[202:205], v[90:93]
	v_mfma_f32_16x16x32_bf16 v[82:85], v[218:221], v[202:205], v[82:85]
	s_add_i32 s6, s6, 1
	s_add_i32 s13, s13, 0xc000
	s_add_i32 s14, s14, 1
	v_lshl_add_u64 v[108:109], v[108:109], 0, s[2:3]
	s_cmp_eq_u32 s13, 0x9c000
	v_lshl_add_u64 v[110:111], v[110:111], 0, s[2:3]
	s_cbranch_scc0 .LBB0_94
	s_waitcnt lgkmcnt(0)
	v_mfma_f32_16x16x32_bf16 v[34:37], v[22:25], v[30:33], v[34:37]
	v_mfma_f32_16x16x32_bf16 v[74:77], v[18:21], v[30:33], v[74:77]
	v_mfma_f32_16x16x32_bf16 v[70:73], v[10:13], v[30:33], v[70:73]
	v_mfma_f32_16x16x32_bf16 v[30:33], v[6:9], v[30:33], v[78:81]
	v_mfma_f32_16x16x32_bf16 v[66:69], v[22:25], v[26:29], v[66:69]
	v_mfma_f32_16x16x32_bf16 v[62:65], v[18:21], v[26:29], v[62:65]
	v_mfma_f32_16x16x32_bf16 v[58:61], v[10:13], v[26:29], v[58:61]
	v_mfma_f32_16x16x32_bf16 v[26:29], v[6:9], v[26:29], v[54:57]
	v_mfma_f32_16x16x32_bf16 v[50:53], v[22:25], v[14:17], v[50:53]
	v_mfma_f32_16x16x32_bf16 v[46:49], v[18:21], v[14:17], v[46:49]
	v_mfma_f32_16x16x32_bf16 v[42:45], v[10:13], v[14:17], v[42:45]
	v_mfma_f32_16x16x32_bf16 v[14:17], v[6:9], v[14:17], v[38:41]
	v_mfma_f32_16x16x32_bf16 v[22:25], v[22:25], v[2:5], v[86:89]
	s_nop 1
	ds_read_b128 v[38:41], v131
	ds_read_b128 v[54:57], v132 offset:2048
	ds_read_b128 v[78:81], v132 offset:4096
	ds_read_b128 v[86:89], v132 offset:6144
	v_mfma_f32_16x16x32_bf16 v[18:21], v[18:21], v[2:5], v[94:97]
	v_mfma_f32_16x16x32_bf16 v[10:13], v[10:13], v[2:5], v[90:93]
	s_nop 2
	ds_read_b128 v[90:93], v133 offset:32768
	ds_read_b128 v[94:97], v134 offset:34816
	ds_read_b128 v[108:111], v134 offset:36864
	ds_read_b128 v[174:177], v134 offset:38912
	v_mfma_f32_16x16x32_bf16 v[2:5], v[6:9], v[2:5], v[82:85]
	s_waitcnt lgkmcnt(0)
	v_mfma_f32_16x16x32_bf16 v[6:9], v[90:93], v[38:41], v[34:37]
	s_waitcnt vmcnt(6)
	s_waitcnt lgkmcnt(0)
	s_barrier
	v_mfma_f32_16x16x32_bf16 v[34:37], v[94:97], v[38:41], v[74:77]
	v_mfma_f32_16x16x32_bf16 v[70:73], v[108:111], v[38:41], v[70:73]
	v_mfma_f32_16x16x32_bf16 v[30:33], v[174:177], v[38:41], v[30:33]
	v_mfma_f32_16x16x32_bf16 v[38:41], v[90:93], v[54:57], v[66:69]
	v_mfma_f32_16x16x32_bf16 v[62:65], v[94:97], v[54:57], v[62:65]
	v_mfma_f32_16x16x32_bf16 v[58:61], v[108:111], v[54:57], v[58:61]
	v_mfma_f32_16x16x32_bf16 v[26:29], v[174:177], v[54:57], v[26:29]
	v_add_u32_e32 v54, v124, v115
	ds_read_b128 v[54:57], v54
	ds_read_b128 v[66:69], v135 offset:2048
	v_mfma_f32_16x16x32_bf16 v[50:53], v[90:93], v[78:81], v[50:53]
	v_mfma_f32_16x16x32_bf16 v[46:49], v[94:97], v[78:81], v[46:49]
	v_mfma_f32_16x16x32_bf16 v[42:45], v[108:111], v[78:81], v[42:45]
	v_mfma_f32_16x16x32_bf16 v[22:25], v[90:93], v[86:89], v[22:25]
	v_add_u32_e32 v90, 0x20800, v164
	v_mfma_f32_16x16x32_bf16 v[18:21], v[94:97], v[86:89], v[18:21]
	v_add_u32_e32 v94, 0x21000, v164
	v_mfma_f32_16x16x32_bf16 v[10:13], v[108:111], v[86:89], v[10:13]
	v_add_u32_e32 v108, 0x21800, v164
	v_mfma_f32_16x16x32_bf16 v[14:17], v[174:177], v[78:81], v[14:17]
	ds_read_b128 v[74:77], v135 offset:4096
	ds_read_b128 v[78:81], v135 offset:6144
	ds_read_b128 v[82:85], v163
	ds_read_b128 v[90:93], v90
	ds_read_b128 v[94:97], v94
	ds_read_b128 v[108:111], v108
	v_mfma_f32_16x16x32_bf16 v[2:5], v[174:177], v[86:89], v[2:5]
	s_waitcnt lgkmcnt(0)
	v_mfma_f32_16x16x32_bf16 v[6:9], v[82:85], v[54:57], v[6:9]
	v_mfma_f32_16x16x32_bf16 v[34:37], v[90:93], v[54:57], v[34:37]
	v_mfma_f32_16x16x32_bf16 v[70:73], v[94:97], v[54:57], v[70:73]
	v_mfma_f32_16x16x32_bf16 v[30:33], v[108:111], v[54:57], v[30:33]
	v_mfma_f32_16x16x32_bf16 v[54:57], v[90:93], v[66:69], v[62:65]
	s_nop 2
	v_add_u32_e32 v62, v124, v119
	v_mfma_f32_16x16x32_bf16 v[38:41], v[82:85], v[66:69], v[38:41]
	v_mfma_f32_16x16x32_bf16 v[58:61], v[94:97], v[66:69], v[58:61]
	v_mfma_f32_16x16x32_bf16 v[26:29], v[108:111], v[66:69], v[26:29]
	v_mfma_f32_16x16x32_bf16 v[50:53], v[82:85], v[74:77], v[50:53]
	v_mfma_f32_16x16x32_bf16 v[46:49], v[90:93], v[74:77], v[46:49]
	v_mfma_f32_16x16x32_bf16 v[42:45], v[94:97], v[74:77], v[42:45]
	v_mfma_f32_16x16x32_bf16 v[14:17], v[108:111], v[74:77], v[14:17]
	v_mfma_f32_16x16x32_bf16 v[22:25], v[82:85], v[78:81], v[22:25]
	ds_read_b128 v[62:65], v62
	ds_read_b128 v[66:69], v165
	ds_read_b128 v[74:77], v166
	ds_read_b128 v[82:85], v167
	v_mfma_f32_16x16x32_bf16 v[18:21], v[90:93], v[78:81], v[18:21]
	v_mfma_f32_16x16x32_bf16 v[10:13], v[94:97], v[78:81], v[10:13]
	ds_read_b128 v[86:89], v168
	ds_read_b128 v[90:93], v169
	ds_read_b128 v[94:97], v170
	ds_read_b128 v[174:177], v171
	v_mfma_f32_16x16x32_bf16 v[2:5], v[108:111], v[78:81], v[2:5]
	s_waitcnt vmcnt(0)
	s_waitcnt lgkmcnt(0)
	v_mfma_f32_16x16x32_bf16 v[6:9], v[86:89], v[62:65], v[6:9]
	s_waitcnt lgkmcnt(0)
	s_barrier
	v_mfma_f32_16x16x32_bf16 v[34:37], v[90:93], v[62:65], v[34:37]
	v_mfma_f32_16x16x32_bf16 v[70:73], v[94:97], v[62:65], v[70:73]
	v_mfma_f32_16x16x32_bf16 v[30:33], v[174:177], v[62:65], v[30:33]
	v_mfma_f32_16x16x32_bf16 v[38:41], v[86:89], v[66:69], v[38:41]
	v_mfma_f32_16x16x32_bf16 v[54:57], v[90:93], v[66:69], v[54:57]
	v_mfma_f32_16x16x32_bf16 v[58:61], v[94:97], v[66:69], v[58:61]
	v_mfma_f32_16x16x32_bf16 v[26:29], v[174:177], v[66:69], v[26:29]
	v_mfma_f32_16x16x32_bf16 v[50:53], v[86:89], v[74:77], v[50:53]
	v_mfma_f32_16x16x32_bf16 v[46:49], v[90:93], v[74:77], v[46:49]
	v_mfma_f32_16x16x32_bf16 v[42:45], v[94:97], v[74:77], v[42:45]
	v_mfma_f32_16x16x32_bf16 v[14:17], v[174:177], v[74:77], v[14:17]
	ds_read_b128 v[62:65], v164 offset:38912
	ds_read_b128 v[66:69], v164 offset:36864
	ds_read_b128 v[74:77], v164 offset:34816
	ds_read_b128 v[78:81], v161 offset:32768
	v_mfma_f32_16x16x32_bf16 v[22:25], v[86:89], v[82:85], v[22:25]
	v_mfma_f32_16x16x32_bf16 v[18:21], v[90:93], v[82:85], v[18:21]
	v_mfma_f32_16x16x32_bf16 v[10:13], v[94:97], v[82:85], v[10:13]
	ds_read_b128 v[86:89], v173 offset:6144
	ds_read_b128 v[90:93], v173 offset:4096
	ds_read_b128 v[94:97], v173 offset:2048
	ds_read_b128 v[108:111], v172
	v_mfma_f32_16x16x32_bf16 v[2:5], v[174:177], v[82:85], v[2:5]
	s_waitcnt lgkmcnt(0)
	v_mfma_f32_16x16x32_bf16 v[38:41], v[78:81], v[94:97], v[38:41]
	v_add_u32_e32 v82, v114, v119
	v_add_u32_e32 v172, v118, v119
	v_mfma_f32_16x16x32_bf16 v[54:57], v[74:77], v[94:97], v[54:57]
	v_mfma_f32_16x16x32_bf16 v[58:61], v[66:69], v[94:97], v[58:61]
	v_mfma_f32_16x16x32_bf16 v[26:29], v[62:65], v[94:97], v[26:29]
	v_add_u32_e32 v94, v117, v119
	v_mfma_f32_16x16x32_bf16 v[50:53], v[78:81], v[90:93], v[50:53]
	v_mfma_f32_16x16x32_bf16 v[46:49], v[74:77], v[90:93], v[46:49]
	v_mfma_f32_16x16x32_bf16 v[42:45], v[66:69], v[90:93], v[42:45]
	v_mfma_f32_16x16x32_bf16 v[14:17], v[62:65], v[90:93], v[14:17]
	v_add_u32_e32 v90, v116, v119
	v_mfma_f32_16x16x32_bf16 v[6:9], v[78:81], v[108:111], v[6:9]
	v_mfma_f32_16x16x32_bf16 v[34:37], v[74:77], v[108:111], v[34:37]
	v_mfma_f32_16x16x32_bf16 v[70:73], v[66:69], v[108:111], v[70:73]
	v_mfma_f32_16x16x32_bf16 v[30:33], v[62:65], v[108:111], v[30:33]
	v_mfma_f32_16x16x32_bf16 v[78:81], v[78:81], v[86:89], v[22:25]
	s_nop 2
	ds_read_b128 v[22:25], v82
	ds_read_b128 v[82:85], v90 offset:2048
	v_mfma_f32_16x16x32_bf16 v[74:77], v[74:77], v[86:89], v[18:21]
	s_nop 2
	ds_read_b128 v[18:21], v90 offset:4096
	ds_read_b128 v[90:93], v90 offset:6144
	v_mfma_f32_16x16x32_bf16 v[66:69], v[66:69], v[86:89], v[10:13]
	s_nop 2
	ds_read_b128 v[10:13], v94 offset:32768
	ds_read_b128 v[94:97], v172 offset:34816
	ds_read_b128 v[108:111], v172 offset:36864
	ds_read_b128 v[172:175], v172 offset:38912
	v_mfma_f32_16x16x32_bf16 v[2:5], v[62:65], v[86:89], v[2:5]
	s_waitcnt vmcnt(0)
	s_waitcnt lgkmcnt(0)
	v_mfma_f32_16x16x32_bf16 v[2:5], v[172:175], v[90:93], v[2:5]
	s_waitcnt lgkmcnt(0)
	s_barrier
	v_mfma_f32_16x16x32_bf16 v[62:65], v[10:13], v[22:25], v[6:9]
	v_mfma_f32_16x16x32_bf16 v[86:89], v[94:97], v[22:25], v[34:37]
	v_mfma_f32_16x16x32_bf16 v[70:73], v[108:111], v[22:25], v[70:73]
	v_mfma_f32_16x16x32_bf16 v[176:179], v[172:175], v[22:25], v[30:33]
	v_mfma_f32_16x16x32_bf16 v[202:205], v[10:13], v[82:85], v[38:41]
	v_mfma_f32_16x16x32_bf16 v[54:57], v[94:97], v[82:85], v[54:57]
	v_mfma_f32_16x16x32_bf16 v[58:61], v[108:111], v[82:85], v[58:61]
	v_mfma_f32_16x16x32_bf16 v[34:37], v[172:175], v[82:85], v[26:29]
	v_mfma_f32_16x16x32_bf16 v[30:33], v[10:13], v[18:21], v[50:53]
	v_mfma_f32_16x16x32_bf16 v[26:29], v[94:97], v[18:21], v[46:49]
	v_mfma_f32_16x16x32_bf16 v[22:25], v[108:111], v[18:21], v[42:45]
	v_mfma_f32_16x16x32_bf16 v[18:21], v[172:175], v[18:21], v[14:17]
	v_mfma_f32_16x16x32_bf16 v[14:17], v[10:13], v[90:93], v[78:81]
	v_mfma_f32_16x16x32_bf16 v[10:13], v[94:97], v[90:93], v[74:77]
	v_mfma_f32_16x16x32_bf16 v[6:9], v[108:111], v[90:93], v[66:69]
	s_mul_hi_i32 s64, s60, 0x2aaaaaab
	s_lshr_b32 s65, s64, 31
	s_ashr_i32 s64, s64, 2
	s_add_i32 s6, s64, s65
	s_mul_i32 s64, s6, 24
	s_sub_i32 s13, s60, s64
	v_readfirstlane_b32 s64, v137
	s_lshr_b32 s64, s64, 6
	s_and_b32 s14, s64, 1
	s_lshr_b32 s64, s64, 1
	s_lshl_b32 s64, s64, 6
	s_lshl_b32 s36, s13, 8
	s_add_i32 s36, s36, s64
	s_lshl_b32 s37, s6, 7
	s_lshl_b32 s64, s14, 6
	s_add_i32 s37, s37, s64
	s_add_i32 s64, s36, 0xfffff000
	s_ashr_i32 s64, s64, 10
	s_add_i32 s64, s64, 1
	s_cmpk_lt_i32 s36, 0x1000
	s_cselect_b32 s52, 0, s64
	v_readlane_b32 s53, v255, 40
	v_and_b32_e32 v250, 63, v137
	v_and_b32_e32 v251, 15, v250
	v_lshrrev_b32_e32 v252, 4, v250
	s_mul_i32 s64, s53, 3
	s_add_i32 s64, s64, s52
	s_mul_i32 s64, s64, 0x6000
	s_add_u32 s22, s94, 0x6300000
	s_addc_u32 s23, s95, 0
	s_add_u32 s22, s22, s64
	s_addc_u32 s23, s23, 0
	s_add_u32 s26, s94, 0x6348000
	s_addc_u32 s27, s95, 0
	v_add_u32_e32 v242, s36, v251
	v_lshlrev_b32_e32 v242, 12, v242
	s_lshl_b32 s64, s37, 2
	v_lshl_add_u32 v242, v252, 4, v242
	v_add_u32_e32 v242, s64, v242
	s_add_i32 s65, s37, 2048
	s_lshl_b32 s65, s65, 2
	v_lshl_add_u32 v246, v252, 4, s65
	v_add_u32_e32 v243, 0x10000, v242
	v_add_u32_e32 v244, 0x20000, v242
	v_add_u32_e32 v245, 0x30000, v242
	global_load_dwordx4 v[226:229], v246, s[22:23]
	global_load_dwordx4 v[230:233], v246, s[22:23] offset:64
	global_load_dwordx4 v[234:237], v246, s[22:23] offset:128
	global_load_dwordx4 v[238:241], v246, s[22:23] offset:192
	global_load_dwordx4 v[38:41], v242, s[26:27]
	global_load_dwordx4 v[42:45], v242, s[26:27] offset:64
	global_load_dwordx4 v[46:49], v242, s[26:27] offset:128
	global_load_dwordx4 v[50:53], v242, s[26:27] offset:192
	global_load_dwordx4 v[66:69], v243, s[26:27]
	global_load_dwordx4 v[74:77], v243, s[26:27] offset:64
	global_load_dwordx4 v[78:81], v243, s[26:27] offset:128
	global_load_dwordx4 v[82:85], v243, s[26:27] offset:192
	global_load_dwordx4 v[90:93], v244, s[26:27]
	global_load_dwordx4 v[94:97], v244, s[26:27] offset:64
	global_load_dwordx4 v[108:111], v244, s[26:27] offset:128
	global_load_dwordx4 v[172:175], v244, s[26:27] offset:192
	global_load_dwordx4 v[206:209], v245, s[26:27]
	global_load_dwordx4 v[210:213], v245, s[26:27] offset:64
	global_load_dwordx4 v[214:217], v245, s[26:27] offset:128
	global_load_dwordx4 v[218:221], v245, s[26:27] offset:192
	v_mov_b32_e32 v248, 0x3fd744fd
	v_mov_b32_e32 v249, 0x3fd744fd
	s_waitcnt vmcnt(12)
	v_pk_mul_f32 v[38:39], v[38:39], v[248:249]
	v_pk_mul_f32 v[40:41], v[40:41], v[248:249]
	v_pk_fma_f32 v[62:63], v[62:63], v[226:227], v[38:39]
	v_pk_fma_f32 v[64:65], v[64:65], v[228:229], v[40:41]
	v_pk_mul_f32 v[42:43], v[42:43], v[248:249]
	v_pk_mul_f32 v[44:45], v[44:45], v[248:249]
	v_pk_fma_f32 v[86:87], v[86:87], v[230:231], v[42:43]
	v_pk_fma_f32 v[88:89], v[88:89], v[232:233], v[44:45]
	v_pk_mul_f32 v[46:47], v[46:47], v[248:249]
	v_pk_mul_f32 v[48:49], v[48:49], v[248:249]
	v_pk_fma_f32 v[70:71], v[70:71], v[234:235], v[46:47]
	v_pk_fma_f32 v[72:73], v[72:73], v[236:237], v[48:49]
	v_pk_mul_f32 v[50:51], v[50:51], v[248:249]
	v_pk_mul_f32 v[52:53], v[52:53], v[248:249]
	v_pk_fma_f32 v[176:177], v[176:177], v[238:239], v[50:51]
	v_pk_fma_f32 v[178:179], v[178:179], v[240:241], v[52:53]
	s_waitcnt vmcnt(8)
	v_pk_mul_f32 v[66:67], v[66:67], v[248:249]
	v_pk_mul_f32 v[68:69], v[68:69], v[248:249]
	v_pk_fma_f32 v[202:203], v[202:203], v[226:227], v[66:67]
	v_pk_fma_f32 v[204:205], v[204:205], v[228:229], v[68:69]
	v_pk_mul_f32 v[74:75], v[74:75], v[248:249]
	v_pk_mul_f32 v[76:77], v[76:77], v[248:249]
	v_pk_fma_f32 v[54:55], v[54:55], v[230:231], v[74:75]
	v_pk_fma_f32 v[56:57], v[56:57], v[232:233], v[76:77]
	v_pk_mul_f32 v[78:79], v[78:79], v[248:249]
	v_pk_mul_f32 v[80:81], v[80:81], v[248:249]
	v_pk_fma_f32 v[58:59], v[58:59], v[234:235], v[78:79]
	v_pk_fma_f32 v[60:61], v[60:61], v[236:237], v[80:81]
	v_pk_mul_f32 v[82:83], v[82:83], v[248:249]
	v_pk_mul_f32 v[84:85], v[84:85], v[248:249]
	v_pk_fma_f32 v[34:35], v[34:35], v[238:239], v[82:83]
	v_pk_fma_f32 v[36:37], v[36:37], v[240:241], v[84:85]
	s_waitcnt vmcnt(4)
	v_pk_mul_f32 v[90:91], v[90:91], v[248:249]
	v_pk_mul_f32 v[92:93], v[92:93], v[248:249]
	v_pk_fma_f32 v[30:31], v[30:31], v[226:227], v[90:91]
	v_pk_fma_f32 v[32:33], v[32:33], v[228:229], v[92:93]
	v_pk_mul_f32 v[94:95], v[94:95], v[248:249]
	v_pk_mul_f32 v[96:97], v[96:97], v[248:249]
	v_pk_fma_f32 v[26:27], v[26:27], v[230:231], v[94:95]
	v_pk_fma_f32 v[28:29], v[28:29], v[232:233], v[96:97]
	v_pk_mul_f32 v[108:109], v[108:109], v[248:249]
	v_pk_mul_f32 v[110:111], v[110:111], v[248:249]
	v_pk_fma_f32 v[22:23], v[22:23], v[234:235], v[108:109]
	v_pk_fma_f32 v[24:25], v[24:25], v[236:237], v[110:111]
	v_pk_mul_f32 v[172:173], v[172:173], v[248:249]
	v_pk_mul_f32 v[174:175], v[174:175], v[248:249]
	v_pk_fma_f32 v[18:19], v[18:19], v[238:239], v[172:173]
	v_pk_fma_f32 v[20:21], v[20:21], v[240:241], v[174:175]
	s_waitcnt vmcnt(0)
	v_pk_mul_f32 v[206:207], v[206:207], v[248:249]
	v_pk_mul_f32 v[208:209], v[208:209], v[248:249]
	v_pk_fma_f32 v[14:15], v[14:15], v[226:227], v[206:207]
	v_pk_fma_f32 v[16:17], v[16:17], v[228:229], v[208:209]
	v_pk_mul_f32 v[210:211], v[210:211], v[248:249]
	v_pk_mul_f32 v[212:213], v[212:213], v[248:249]
	v_pk_fma_f32 v[10:11], v[10:11], v[230:231], v[210:211]
	v_pk_fma_f32 v[12:13], v[12:13], v[232:233], v[212:213]
	v_pk_mul_f32 v[214:215], v[214:215], v[248:249]
	v_pk_mul_f32 v[216:217], v[216:217], v[248:249]
	v_pk_fma_f32 v[6:7], v[6:7], v[234:235], v[214:215]
	v_pk_fma_f32 v[8:9], v[8:9], v[236:237], v[216:217]
	v_pk_mul_f32 v[218:219], v[218:219], v[248:249]
	v_pk_mul_f32 v[220:221], v[220:221], v[248:249]
	v_pk_fma_f32 v[2:3], v[2:3], v[238:239], v[218:219]
	v_pk_fma_f32 v[4:5], v[4:5], v[240:241], v[220:221]
	v_pk_mul_f32 v[208:209], v[62:63], v[62:63]
	v_pk_add_f32 v[206:207], v[62:63], v[64:65]
	v_pk_fma_f32 v[208:209], v[64:65], v[64:65], v[208:209]
	v_pk_add_f32 v[206:207], v[206:207], v[86:87]
	v_pk_fma_f32 v[208:209], v[86:87], v[86:87], v[208:209]
	v_pk_add_f32 v[206:207], v[206:207], v[88:89]
	v_pk_fma_f32 v[208:209], v[88:89], v[88:89], v[208:209]
	v_pk_add_f32 v[206:207], v[206:207], v[70:71]
	v_pk_fma_f32 v[208:209], v[70:71], v[70:71], v[208:209]
	v_pk_add_f32 v[206:207], v[206:207], v[72:73]
	v_pk_fma_f32 v[208:209], v[72:73], v[72:73], v[208:209]
	v_pk_add_f32 v[206:207], v[206:207], v[176:177]
	v_pk_fma_f32 v[208:209], v[176:177], v[176:177], v[208:209]
	v_pk_add_f32 v[206:207], v[206:207], v[178:179]
	v_pk_fma_f32 v[208:209], v[178:179], v[178:179], v[208:209]
	v_add_f32_e32 v206, v206, v207
	v_add_f32_e32 v208, v208, v209
	v_pk_mul_f32 v[212:213], v[202:203], v[202:203]
	v_pk_add_f32 v[210:211], v[202:203], v[204:205]
	v_pk_fma_f32 v[212:213], v[204:205], v[204:205], v[212:213]
	v_pk_add_f32 v[210:211], v[210:211], v[54:55]
	v_pk_fma_f32 v[212:213], v[54:55], v[54:55], v[212:213]
	v_pk_add_f32 v[210:211], v[210:211], v[56:57]
	v_pk_fma_f32 v[212:213], v[56:57], v[56:57], v[212:213]
	v_pk_add_f32 v[210:211], v[210:211], v[58:59]
	v_pk_fma_f32 v[212:213], v[58:59], v[58:59], v[212:213]
	v_pk_add_f32 v[210:211], v[210:211], v[60:61]
	v_pk_fma_f32 v[212:213], v[60:61], v[60:61], v[212:213]
	v_pk_add_f32 v[210:211], v[210:211], v[34:35]
	v_pk_fma_f32 v[212:213], v[34:35], v[34:35], v[212:213]
	v_pk_add_f32 v[210:211], v[210:211], v[36:37]
	v_pk_fma_f32 v[212:213], v[36:37], v[36:37], v[212:213]
	v_add_f32_e32 v210, v210, v211
	v_add_f32_e32 v212, v212, v213
	v_pk_mul_f32 v[216:217], v[30:31], v[30:31]
	v_pk_add_f32 v[214:215], v[30:31], v[32:33]
	v_pk_fma_f32 v[216:217], v[32:33], v[32:33], v[216:217]
	v_pk_add_f32 v[214:215], v[214:215], v[26:27]
	v_pk_fma_f32 v[216:217], v[26:27], v[26:27], v[216:217]
	v_pk_add_f32 v[214:215], v[214:215], v[28:29]
	v_pk_fma_f32 v[216:217], v[28:29], v[28:29], v[216:217]
	v_pk_add_f32 v[214:215], v[214:215], v[22:23]
	v_pk_fma_f32 v[216:217], v[22:23], v[22:23], v[216:217]
	v_pk_add_f32 v[214:215], v[214:215], v[24:25]
	v_pk_fma_f32 v[216:217], v[24:25], v[24:25], v[216:217]
	v_pk_add_f32 v[214:215], v[214:215], v[18:19]
	v_pk_fma_f32 v[216:217], v[18:19], v[18:19], v[216:217]
	v_pk_add_f32 v[214:215], v[214:215], v[20:21]
	v_pk_fma_f32 v[216:217], v[20:21], v[20:21], v[216:217]
	v_add_f32_e32 v214, v214, v215
	v_add_f32_e32 v216, v216, v217
	v_pk_mul_f32 v[220:221], v[14:15], v[14:15]
	v_pk_add_f32 v[218:219], v[14:15], v[16:17]
	v_pk_fma_f32 v[220:221], v[16:17], v[16:17], v[220:221]
	v_pk_add_f32 v[218:219], v[218:219], v[10:11]
	v_pk_fma_f32 v[220:221], v[10:11], v[10:11], v[220:221]
	v_pk_add_f32 v[218:219], v[218:219], v[12:13]
	v_pk_fma_f32 v[220:221], v[12:13], v[12:13], v[220:221]
	v_pk_add_f32 v[218:219], v[218:219], v[6:7]
	v_pk_fma_f32 v[220:221], v[6:7], v[6:7], v[220:221]
	v_pk_add_f32 v[218:219], v[218:219], v[8:9]
	v_pk_fma_f32 v[220:221], v[8:9], v[8:9], v[220:221]
	v_pk_add_f32 v[218:219], v[218:219], v[2:3]
	v_pk_fma_f32 v[220:221], v[2:3], v[2:3], v[220:221]
	v_pk_add_f32 v[218:219], v[218:219], v[4:5]
	v_pk_fma_f32 v[220:221], v[4:5], v[4:5], v[220:221]
	v_add_f32_e32 v218, v218, v219
	v_add_f32_e32 v220, v220, v221
	s_nop 1
	v_permlane16_swap_b32_e32 v206, v210
	v_permlane16_swap_b32_e32 v214, v218
	v_permlane16_swap_b32_e32 v208, v212
	v_permlane16_swap_b32_e32 v216, v220
	v_add_f32_e32 v206, v206, v210
	v_add_f32_e32 v214, v214, v218
	v_add_f32_e32 v208, v208, v212
	v_add_f32_e32 v216, v216, v220
	s_nop 1
	v_permlane32_swap_b32_e32 v206, v214
	v_permlane32_swap_b32_e32 v208, v216
	v_add_f32_e32 v248, v206, v214
	v_add_f32_e32 v249, v208, v216
	s_add_u32 s44, s94, 0x11e5e100
	s_addc_u32 s45, s95, 0
	v_add_u32_e32 v247, s36, v250
	v_lshlrev_b32_e32 v247, 7, v247
	s_lshl_b32 s64, s6, 4
	s_lshl_b32 s65, s14, 3
	s_add_i32 s64, s64, s65
	v_add_u32_e32 v246, s64, v247
	global_store_dwordx2 v246, v[248:249], s[44:45] sc1
	v_readlane_b32 s46, v253, 11
	v_readlane_b32 s47, v253, 12
	v_readlane_b32 s48, v253, 13
	v_readlane_b32 s49, v253, 14
	s_lshl_b32 s64, s53, 10
	s_add_i32 s64, s64, s37
	s_lshl_b32 s64, s64, 2
	v_lshl_add_u32 v222, v252, 4, s64
	s_nop 3
	global_load_dwordx4 v[66:69], v222, s[46:47]
	global_load_dwordx4 v[74:77], v222, s[46:47] offset:64
	global_load_dwordx4 v[78:81], v222, s[46:47] offset:128
	global_load_dwordx4 v[82:85], v222, s[46:47] offset:192
	global_load_dwordx4 v[90:93], v222, s[48:49]
	global_load_dwordx4 v[94:97], v222, s[48:49] offset:64
	global_load_dwordx4 v[108:111], v222, s[48:49] offset:128
	global_load_dwordx4 v[172:175], v222, s[48:49] offset:192
	s_waitcnt vmcnt(8)
	s_barrier
	v_cmp_eq_u32_e64 s[46:47], 0, v137
	s_nop 3
	s_and_saveexec_b64 s[48:49], s[46:47]
	s_cbranch_execz .Lln1_xdone
	s_mul_i32 s64, s53, 384
	s_lshl_b32 s65, s13, 2
	s_add_i32 s64, s64, s65
	s_add_u32 s46, s94, 0x11e5d700
	s_addc_u32 s47, s95, 0
	s_add_u32 s46, s46, s64
	s_addc_u32 s47, s47, 0
	v_mov_b32_e32 v248, 1
	s_mov_b32 s65, 0x100000
	global_atomic_add v1, v248, s[46:47]
.Lln1_poll:
	global_load_dword v248, v1, s[46:47] sc1
	s_waitcnt vmcnt(0)
	v_cmp_lt_u32_e32 vcc, 7, v248
	s_cbranch_vccnz .Lln1_xdone
	s_sleep 1
	s_add_i32 s65, s65, -1
	s_cmp_lg_u32 s65, 0
	s_cbranch_scc1 .Lln1_poll
.Lln1_xdone:
	s_or_b64 exec, exec, s[48:49]
	s_barrier
	global_load_dwordx4 v[226:229], v247, s[44:45] sc1
	global_load_dwordx4 v[230:233], v247, s[44:45] offset:16 sc1
	global_load_dwordx4 v[234:237], v247, s[44:45] offset:32 sc1
	global_load_dwordx4 v[238:241], v247, s[44:45] offset:48 sc1
	global_load_dwordx4 v[38:41], v247, s[44:45] offset:64 sc1
	global_load_dwordx4 v[42:45], v247, s[44:45] offset:80 sc1
	global_load_dwordx4 v[46:49], v247, s[44:45] offset:96 sc1
	global_load_dwordx4 v[50:53], v247, s[44:45] offset:112 sc1
	s_waitcnt vmcnt(0)
	v_add_f32_e32 v206, 0, v226
	v_add_f32_e32 v207, 0, v227
	v_add_f32_e32 v206, v206, v228
	v_add_f32_e32 v207, v207, v229
	v_add_f32_e32 v206, v206, v230
	v_add_f32_e32 v207, v207, v231
	v_add_f32_e32 v206, v206, v232
	v_add_f32_e32 v207, v207, v233
	v_add_f32_e32 v206, v206, v234
	v_add_f32_e32 v207, v207, v235
	v_add_f32_e32 v206, v206, v236
	v_add_f32_e32 v207, v207, v237
	v_add_f32_e32 v206, v206, v238
	v_add_f32_e32 v207, v207, v239
	v_add_f32_e32 v206, v206, v240
	v_add_f32_e32 v207, v207, v241
	v_add_f32_e32 v206, v206, v38
	v_add_f32_e32 v207, v207, v39
	v_add_f32_e32 v206, v206, v40
	v_add_f32_e32 v207, v207, v41
	v_add_f32_e32 v206, v206, v42
	v_add_f32_e32 v207, v207, v43
	v_add_f32_e32 v206, v206, v44
	v_add_f32_e32 v207, v207, v45
	v_add_f32_e32 v206, v206, v46
	v_add_f32_e32 v207, v207, v47
	v_add_f32_e32 v206, v206, v48
	v_add_f32_e32 v207, v207, v49
	v_add_f32_e32 v206, v206, v50
	v_add_f32_e32 v207, v207, v51
	v_add_f32_e32 v206, v206, v52
	v_add_f32_e32 v207, v207, v53
	s_add_i32 s64, s37, 3072
	s_lshl_b32 s64, s64, 2
	v_lshl_add_u32 v222, v252, 4, s64
	v_add_u32_e32 v246, 0x1000, v222
	global_load_dwordx4 v[226:229], v222, s[22:23]
	global_load_dwordx4 v[230:233], v222, s[22:23] offset:64
	global_load_dwordx4 v[234:237], v222, s[22:23] offset:128
	global_load_dwordx4 v[238:241], v222, s[22:23] offset:192
	global_load_dwordx4 v[38:41], v246, s[22:23]
	global_load_dwordx4 v[42:45], v246, s[22:23] offset:64
	global_load_dwordx4 v[46:49], v246, s[22:23] offset:128
	global_load_dwordx4 v[50:53], v246, s[22:23] offset:192
	v_mul_f32_e32 v208, 0x3a800000, v206
	v_mul_f32_e32 v209, v208, v208
	v_mov_b32_e32 v216, 0x3a800000
	v_fma_f32 v209, v207, v216, -v209
	v_max_f32_e32 v209, 0, v209
	v_add_f32_e32 v209, 0x3727c5ac, v209
	v_rsq_f32_e32 v209, v209
	v_mov_b32_e32 v210, v208
	v_mov_b32_e32 v211, v208
	v_mov_b32_e32 v214, v209
	v_mov_b32_e32 v215, v209
	s_nop 1
	v_permlane16_swap_b32_e32 v210, v211
	v_permlane16_swap_b32_e32 v214, v215
	v_mov_b32_e32 v212, v210
	v_mov_b32_e32 v213, v211
	v_mov_b32_e32 v216, v214
	v_mov_b32_e32 v217, v215
	s_nop 1
	v_permlane32_swap_b32_e32 v210, v212
	v_permlane32_swap_b32_e32 v211, v213
	v_permlane32_swap_b32_e32 v214, v216
	v_permlane32_swap_b32_e32 v215, v217
	v_sub_f32_e32 v62, v62, v210
	v_sub_f32_e32 v63, v63, v210
	v_sub_f32_e32 v64, v64, v210
	v_sub_f32_e32 v65, v65, v210
	v_mul_f32_e32 v62, v214, v62
	v_mul_f32_e32 v63, v214, v63
	v_mul_f32_e32 v64, v214, v64
	v_mul_f32_e32 v65, v214, v65
	v_fma_f32 v62, v66, v62, v90
	v_fma_f32 v63, v67, v63, v91
	v_fma_f32 v64, v68, v64, v92
	v_fma_f32 v65, v69, v65, v93
	global_store_dwordx4 v242, v[62:65], s[26:27]
	v_sub_f32_e32 v86, v86, v210
	v_sub_f32_e32 v87, v87, v210
	v_sub_f32_e32 v88, v88, v210
	v_sub_f32_e32 v89, v89, v210
	v_mul_f32_e32 v86, v214, v86
	v_mul_f32_e32 v87, v214, v87
	v_mul_f32_e32 v88, v214, v88
	v_mul_f32_e32 v89, v214, v89
	v_fma_f32 v86, v74, v86, v94
	v_fma_f32 v87, v75, v87, v95
	v_fma_f32 v88, v76, v88, v96
	v_fma_f32 v89, v77, v89, v97
	global_store_dwordx4 v242, v[86:89], s[26:27] offset:64
	v_sub_f32_e32 v70, v70, v210
	v_sub_f32_e32 v71, v71, v210
	v_sub_f32_e32 v72, v72, v210
	v_sub_f32_e32 v73, v73, v210
	v_mul_f32_e32 v70, v214, v70
	v_mul_f32_e32 v71, v214, v71
	v_mul_f32_e32 v72, v214, v72
	v_mul_f32_e32 v73, v214, v73
	v_fma_f32 v70, v78, v70, v108
	v_fma_f32 v71, v79, v71, v109
	v_fma_f32 v72, v80, v72, v110
	v_fma_f32 v73, v81, v73, v111
	global_store_dwordx4 v242, v[70:73], s[26:27] offset:128
	v_sub_f32_e32 v176, v176, v210
	v_sub_f32_e32 v177, v177, v210
	v_sub_f32_e32 v178, v178, v210
	v_sub_f32_e32 v179, v179, v210
	v_mul_f32_e32 v176, v214, v176
	v_mul_f32_e32 v177, v214, v177
	v_mul_f32_e32 v178, v214, v178
	v_mul_f32_e32 v179, v214, v179
	v_fma_f32 v176, v82, v176, v172
	v_fma_f32 v177, v83, v177, v173
	v_fma_f32 v178, v84, v178, v174
	v_fma_f32 v179, v85, v179, v175
	global_store_dwordx4 v242, v[176:179], s[26:27] offset:192
	v_sub_f32_e32 v202, v202, v211
	v_sub_f32_e32 v203, v203, v211
	v_sub_f32_e32 v204, v204, v211
	v_sub_f32_e32 v205, v205, v211
	v_mul_f32_e32 v202, v215, v202
	v_mul_f32_e32 v203, v215, v203
	v_mul_f32_e32 v204, v215, v204
	v_mul_f32_e32 v205, v215, v205
	v_fma_f32 v202, v66, v202, v90
	v_fma_f32 v203, v67, v203, v91
	v_fma_f32 v204, v68, v204, v92
	v_fma_f32 v205, v69, v205, v93
	global_store_dwordx4 v243, v[202:205], s[26:27]
	v_sub_f32_e32 v54, v54, v211
	v_sub_f32_e32 v55, v55, v211
	v_sub_f32_e32 v56, v56, v211
	v_sub_f32_e32 v57, v57, v211
	v_mul_f32_e32 v54, v215, v54
	v_mul_f32_e32 v55, v215, v55
	v_mul_f32_e32 v56, v215, v56
	v_mul_f32_e32 v57, v215, v57
	v_fma_f32 v54, v74, v54, v94
	v_fma_f32 v55, v75, v55, v95
	v_fma_f32 v56, v76, v56, v96
	v_fma_f32 v57, v77, v57, v97
	global_store_dwordx4 v243, v[54:57], s[26:27] offset:64
	v_sub_f32_e32 v58, v58, v211
	v_sub_f32_e32 v59, v59, v211
	v_sub_f32_e32 v60, v60, v211
	v_sub_f32_e32 v61, v61, v211
	v_mul_f32_e32 v58, v215, v58
	v_mul_f32_e32 v59, v215, v59
	v_mul_f32_e32 v60, v215, v60
	v_mul_f32_e32 v61, v215, v61
	v_fma_f32 v58, v78, v58, v108
	v_fma_f32 v59, v79, v59, v109
	v_fma_f32 v60, v80, v60, v110
	v_fma_f32 v61, v81, v61, v111
	global_store_dwordx4 v243, v[58:61], s[26:27] offset:128
	v_sub_f32_e32 v34, v34, v211
	v_sub_f32_e32 v35, v35, v211
	v_sub_f32_e32 v36, v36, v211
	v_sub_f32_e32 v37, v37, v211
	v_mul_f32_e32 v34, v215, v34
	v_mul_f32_e32 v35, v215, v35
	v_mul_f32_e32 v36, v215, v36
	v_mul_f32_e32 v37, v215, v37
	v_fma_f32 v34, v82, v34, v172
	v_fma_f32 v35, v83, v35, v173
	v_fma_f32 v36, v84, v36, v174
	v_fma_f32 v37, v85, v37, v175
	global_store_dwordx4 v243, v[34:37], s[26:27] offset:192
	v_sub_f32_e32 v30, v30, v212
	v_sub_f32_e32 v31, v31, v212
	v_sub_f32_e32 v32, v32, v212
	v_sub_f32_e32 v33, v33, v212
	v_mul_f32_e32 v30, v216, v30
	v_mul_f32_e32 v31, v216, v31
	v_mul_f32_e32 v32, v216, v32
	v_mul_f32_e32 v33, v216, v33
	v_fma_f32 v30, v66, v30, v90
	v_fma_f32 v31, v67, v31, v91
	v_fma_f32 v32, v68, v32, v92
	v_fma_f32 v33, v69, v33, v93
	global_store_dwordx4 v244, v[30:33], s[26:27]
	v_sub_f32_e32 v26, v26, v212
	v_sub_f32_e32 v27, v27, v212
	v_sub_f32_e32 v28, v28, v212
	v_sub_f32_e32 v29, v29, v212
	v_mul_f32_e32 v26, v216, v26
	v_mul_f32_e32 v27, v216, v27
	v_mul_f32_e32 v28, v216, v28
	v_mul_f32_e32 v29, v216, v29
	v_fma_f32 v26, v74, v26, v94
	v_fma_f32 v27, v75, v27, v95
	v_fma_f32 v28, v76, v28, v96
	v_fma_f32 v29, v77, v29, v97
	global_store_dwordx4 v244, v[26:29], s[26:27] offset:64
	v_sub_f32_e32 v22, v22, v212
	v_sub_f32_e32 v23, v23, v212
	v_sub_f32_e32 v24, v24, v212
	v_sub_f32_e32 v25, v25, v212
	v_mul_f32_e32 v22, v216, v22
	v_mul_f32_e32 v23, v216, v23
	v_mul_f32_e32 v24, v216, v24
	v_mul_f32_e32 v25, v216, v25
	v_fma_f32 v22, v78, v22, v108
	v_fma_f32 v23, v79, v23, v109
	v_fma_f32 v24, v80, v24, v110
	v_fma_f32 v25, v81, v25, v111
	global_store_dwordx4 v244, v[22:25], s[26:27] offset:128
	v_sub_f32_e32 v18, v18, v212
	v_sub_f32_e32 v19, v19, v212
	v_sub_f32_e32 v20, v20, v212
	v_sub_f32_e32 v21, v21, v212
	v_mul_f32_e32 v18, v216, v18
	v_mul_f32_e32 v19, v216, v19
	v_mul_f32_e32 v20, v216, v20
	v_mul_f32_e32 v21, v216, v21
	v_fma_f32 v18, v82, v18, v172
	v_fma_f32 v19, v83, v19, v173
	v_fma_f32 v20, v84, v20, v174
	v_fma_f32 v21, v85, v21, v175
	global_store_dwordx4 v244, v[18:21], s[26:27] offset:192
	v_sub_f32_e32 v14, v14, v213
	v_sub_f32_e32 v15, v15, v213
	v_sub_f32_e32 v16, v16, v213
	v_sub_f32_e32 v17, v17, v213
	v_mul_f32_e32 v14, v217, v14
	v_mul_f32_e32 v15, v217, v15
	v_mul_f32_e32 v16, v217, v16
	v_mul_f32_e32 v17, v217, v17
	v_fma_f32 v14, v66, v14, v90
	v_fma_f32 v15, v67, v15, v91
	v_fma_f32 v16, v68, v16, v92
	v_fma_f32 v17, v69, v17, v93
	global_store_dwordx4 v245, v[14:17], s[26:27]
	v_sub_f32_e32 v10, v10, v213
	v_sub_f32_e32 v11, v11, v213
	v_sub_f32_e32 v12, v12, v213
	v_sub_f32_e32 v13, v13, v213
	v_mul_f32_e32 v10, v217, v10
	v_mul_f32_e32 v11, v217, v11
	v_mul_f32_e32 v12, v217, v12
	v_mul_f32_e32 v13, v217, v13
	v_fma_f32 v10, v74, v10, v94
	v_fma_f32 v11, v75, v11, v95
	v_fma_f32 v12, v76, v12, v96
	v_fma_f32 v13, v77, v13, v97
	global_store_dwordx4 v245, v[10:13], s[26:27] offset:64
	v_sub_f32_e32 v6, v6, v213
	v_sub_f32_e32 v7, v7, v213
	v_sub_f32_e32 v8, v8, v213
	v_sub_f32_e32 v9, v9, v213
	v_mul_f32_e32 v6, v217, v6
	v_mul_f32_e32 v7, v217, v7
	v_mul_f32_e32 v8, v217, v8
	v_mul_f32_e32 v9, v217, v9
	v_fma_f32 v6, v78, v6, v108
	v_fma_f32 v7, v79, v7, v109
	v_fma_f32 v8, v80, v8, v110
	v_fma_f32 v9, v81, v9, v111
	global_store_dwordx4 v245, v[6:9], s[26:27] offset:128
	v_sub_f32_e32 v2, v2, v213
	v_sub_f32_e32 v3, v3, v213
	v_sub_f32_e32 v4, v4, v213
	v_sub_f32_e32 v5, v5, v213
	v_mul_f32_e32 v2, v217, v2
	v_mul_f32_e32 v3, v217, v3
	v_mul_f32_e32 v4, v217, v4
	v_mul_f32_e32 v5, v217, v5
	v_fma_f32 v2, v82, v2, v172
	v_fma_f32 v3, v83, v3, v173
	v_fma_f32 v4, v84, v4, v174
	v_fma_f32 v5, v85, v5, v175
	global_store_dwordx4 v245, v[2:5], s[26:27] offset:192
	s_add_u32 s44, s94, 0x7b48000
	s_addc_u32 s45, s95, 0
	s_waitcnt vmcnt(16)
	v_add_f32_e32 v38, 1.0, v38
	v_add_f32_e32 v39, 1.0, v39
	v_add_f32_e32 v40, 1.0, v40
	v_add_f32_e32 v41, 1.0, v41
	v_add_f32_e32 v42, 1.0, v42
	v_add_f32_e32 v43, 1.0, v43
	v_add_f32_e32 v44, 1.0, v44
	v_add_f32_e32 v45, 1.0, v45
	v_add_f32_e32 v46, 1.0, v46
	v_add_f32_e32 v47, 1.0, v47
	v_add_f32_e32 v48, 1.0, v48
	v_add_f32_e32 v49, 1.0, v49
	v_add_f32_e32 v50, 1.0, v50
	v_add_f32_e32 v51, 1.0, v51
	v_add_f32_e32 v52, 1.0, v52
	v_add_f32_e32 v53, 1.0, v53
	v_lshrrev_b32_e32 v218, 1, v242
	v_lshrrev_b32_e32 v219, 1, v243
	v_lshrrev_b32_e32 v220, 1, v244
	v_lshrrev_b32_e32 v221, 1, v245
	v_fma_f32 v62, v38, v62, v226
	v_fma_f32 v63, v39, v63, v227
	v_fma_f32 v64, v40, v64, v228
	v_fma_f32 v65, v41, v65, v229
	v_cvt_pk_bf16_f32 v62, v62, v63
	v_cvt_pk_bf16_f32 v63, v64, v65
	global_store_dwordx2 v218, v[62:63], s[44:45]
	v_fma_f32 v86, v42, v86, v230
	v_fma_f32 v87, v43, v87, v231
	v_fma_f32 v88, v44, v88, v232
	v_fma_f32 v89, v45, v89, v233
	v_cvt_pk_bf16_f32 v86, v86, v87
	v_cvt_pk_bf16_f32 v87, v88, v89
	global_store_dwordx2 v218, v[86:87], s[44:45] offset:32
	v_fma_f32 v70, v46, v70, v234
	v_fma_f32 v71, v47, v71, v235
	v_fma_f32 v72, v48, v72, v236
	v_fma_f32 v73, v49, v73, v237
	v_cvt_pk_bf16_f32 v70, v70, v71
	v_cvt_pk_bf16_f32 v71, v72, v73
	global_store_dwordx2 v218, v[70:71], s[44:45] offset:64
	v_fma_f32 v176, v50, v176, v238
	v_fma_f32 v177, v51, v177, v239
	v_fma_f32 v178, v52, v178, v240
	v_fma_f32 v179, v53, v179, v241
	v_cvt_pk_bf16_f32 v176, v176, v177
	v_cvt_pk_bf16_f32 v177, v178, v179
	global_store_dwordx2 v218, v[176:177], s[44:45] offset:96
	v_fma_f32 v202, v38, v202, v226
	v_fma_f32 v203, v39, v203, v227
	v_fma_f32 v204, v40, v204, v228
	v_fma_f32 v205, v41, v205, v229
	v_cvt_pk_bf16_f32 v202, v202, v203
	v_cvt_pk_bf16_f32 v203, v204, v205
	global_store_dwordx2 v219, v[202:203], s[44:45]
	v_fma_f32 v54, v42, v54, v230
	v_fma_f32 v55, v43, v55, v231
	v_fma_f32 v56, v44, v56, v232
	v_fma_f32 v57, v45, v57, v233
	v_cvt_pk_bf16_f32 v54, v54, v55
	v_cvt_pk_bf16_f32 v55, v56, v57
	global_store_dwordx2 v219, v[54:55], s[44:45] offset:32
	v_fma_f32 v58, v46, v58, v234
	v_fma_f32 v59, v47, v59, v235
	v_fma_f32 v60, v48, v60, v236
	v_fma_f32 v61, v49, v61, v237
	v_cvt_pk_bf16_f32 v58, v58, v59
	v_cvt_pk_bf16_f32 v59, v60, v61
	global_store_dwordx2 v219, v[58:59], s[44:45] offset:64
	v_fma_f32 v34, v50, v34, v238
	v_fma_f32 v35, v51, v35, v239
	v_fma_f32 v36, v52, v36, v240
	v_fma_f32 v37, v53, v37, v241
	v_cvt_pk_bf16_f32 v34, v34, v35
	v_cvt_pk_bf16_f32 v35, v36, v37
	global_store_dwordx2 v219, v[34:35], s[44:45] offset:96
	v_fma_f32 v30, v38, v30, v226
	v_fma_f32 v31, v39, v31, v227
	v_fma_f32 v32, v40, v32, v228
	v_fma_f32 v33, v41, v33, v229
	v_cvt_pk_bf16_f32 v30, v30, v31
	v_cvt_pk_bf16_f32 v31, v32, v33
	global_store_dwordx2 v220, v[30:31], s[44:45]
	v_fma_f32 v26, v42, v26, v230
	v_fma_f32 v27, v43, v27, v231
	v_fma_f32 v28, v44, v28, v232
	v_fma_f32 v29, v45, v29, v233
	v_cvt_pk_bf16_f32 v26, v26, v27
	v_cvt_pk_bf16_f32 v27, v28, v29
	global_store_dwordx2 v220, v[26:27], s[44:45] offset:32
	v_fma_f32 v22, v46, v22, v234
	v_fma_f32 v23, v47, v23, v235
	v_fma_f32 v24, v48, v24, v236
	v_fma_f32 v25, v49, v25, v237
	v_cvt_pk_bf16_f32 v22, v22, v23
	v_cvt_pk_bf16_f32 v23, v24, v25
	global_store_dwordx2 v220, v[22:23], s[44:45] offset:64
	v_fma_f32 v18, v50, v18, v238
	v_fma_f32 v19, v51, v19, v239
	v_fma_f32 v20, v52, v20, v240
	v_fma_f32 v21, v53, v21, v241
	v_cvt_pk_bf16_f32 v18, v18, v19
	v_cvt_pk_bf16_f32 v19, v20, v21
	global_store_dwordx2 v220, v[18:19], s[44:45] offset:96
	v_fma_f32 v14, v38, v14, v226
	v_fma_f32 v15, v39, v15, v227
	v_fma_f32 v16, v40, v16, v228
	v_fma_f32 v17, v41, v17, v229
	v_cvt_pk_bf16_f32 v14, v14, v15
	v_cvt_pk_bf16_f32 v15, v16, v17
	global_store_dwordx2 v221, v[14:15], s[44:45]
	v_fma_f32 v10, v42, v10, v230
	v_fma_f32 v11, v43, v11, v231
	v_fma_f32 v12, v44, v12, v232
	v_fma_f32 v13, v45, v13, v233
	v_cvt_pk_bf16_f32 v10, v10, v11
	v_cvt_pk_bf16_f32 v11, v12, v13
	global_store_dwordx2 v221, v[10:11], s[44:45] offset:32
	v_fma_f32 v6, v46, v6, v234
	v_fma_f32 v7, v47, v7, v235
	v_fma_f32 v8, v48, v8, v236
	v_fma_f32 v9, v49, v9, v237
	v_cvt_pk_bf16_f32 v6, v6, v7
	v_cvt_pk_bf16_f32 v7, v8, v9
	global_store_dwordx2 v221, v[6:7], s[44:45] offset:64
	v_fma_f32 v2, v50, v2, v238
	v_fma_f32 v3, v51, v3, v239
	v_fma_f32 v4, v52, v4, v240
	v_fma_f32 v5, v53, v5, v241
	v_cvt_pk_bf16_f32 v2, v2, v3
	v_cvt_pk_bf16_f32 v3, v4, v5
	global_store_dwordx2 v221, v[2:3], s[44:45] offset:96
	v_readlane_b32 s78, v255, 33
	v_readlane_b32 s79, v255, 34
	s_barrier
	s_load_dword s6, s[78:79], 0x0
	s_mov_b64 s[76:77], 0x7b4c180
	s_mov_b64 s[68:69], 0x7b54180
	s_mov_b64 s[74:75], 0x68800
	s_waitcnt lgkmcnt(0)
	s_add_i32 s60, s6, s60
	s_cmpk_gt_i32 s60, 0xbf
	s_cbranch_scc0 .LBB0_93
